# v42 + EpiLn stage-4 gamma/beta batch only
# speedup vs baseline: 1.0130x; 1.0033x over previous
; __device__ __forceinline__ unsigned pk2(float lo, float hi) { f32x2_t v = {lo, hi}; bf16x2_t b = __builtin_convertvector(v, bf16x2_t); return __builtin_bit_cast(unsigned, b); }
;     __device__ __forceinline__ void fused(f32x4 (&acc)[2][2][4][2], const Unit& u, int wr, int wc, int fr, int fq, PG8_LAS unsigned char* lds, int wid, int lane) const {
;     ...
; #pragma unroll
;         for (int bj = 0; bj < 2; ++bj) {
;             const int col = u.pn * 256 + bj * 128 + wc * 32 + fq * 8;
;             float gg[8], bb[8]; ld8f32(gam + col, gg); ld8f32(bet + col, bb);
; #pragma unroll
;             for (int ai = 0; ai < 2; ++ai)
; #pragma unroll
;                 for (int m = 0; m < 4; ++m) {
;                     const int rl = ai * 128 + wr * 64 + m * 16 + fr;
;                     const float mu = S[rl * 2], rs = S[rl * 2 + 1];
;                     const f32x4 v0 = acc[ai][bj][m][0], v1 = acc[ai][bj][m][1];
;                     float y[8];
; #pragma unroll
;                     for (int j = 0; j < 4; ++j) { y[j] = (v0[j] - mu) * rs * gg[j] + bb[j]; y[4 + j] = (v1[j] - mu) * rs * gg[4 + j] + bb[4 + j]; }
;                     const size_t off = (size_t)(u.pm * 256 + rl) * 1024 + col;
;                     if (of32) { *(float4*)(of32 + off) = make_float4(y[0], y[1], y[2], y[3]); *(float4*)(of32 + off + 4) = make_float4(y[4], y[5], y[6], y[7]); }
;                     if (obf) { uint4 o; o.x = pk2(y[0], y[1]); o.y = pk2(y[2], y[3]); o.z = pk2(y[4], y[5]); o.w = pk2(y[6], y[7]); *(uint4*)(obf + off) = o; }
;                 }
;         }
.LBB0_1069:
	s_or_b64 exec, exec, s[18:19]
	v_or_b32_e32 v0, s9, v2
	v_or_b32_e32 v192, s8, v0
	v_ashrrev_i32_e32 v193, 31, v192
	v_lshlrev_b64 v[0:1], 2, v[192:193]
	v_lshl_add_u64 v[140:141], s[0:1], 0, v[0:1]
	s_waitcnt lgkmcnt(0)
	s_barrier
	v_lshl_add_u64 v[176:177], s[4:5], 0, v[0:1]
	global_load_dwordx4 v[0:3], v[140:141], off offset:16
	global_load_dwordx4 v[4:7], v[140:141], off
	global_load_dwordx4 v[12:15], v[176:177], off
	global_load_dwordx4 v[8:11], v[176:177], off offset:16
	global_load_dwordx4 v[204:207], v[176:177], off offset:512
	global_load_dwordx4 v[208:211], v[140:141], off offset:512
	global_load_dwordx4 v[212:215], v[140:141], off offset:528
	global_load_dwordx4 v[216:219], v[176:177], off offset:528
	v_lshl_add_u32 v129, v129, 3, 0
	v_lshl_add_u64 v[196:197], s[14:15], 0, v[142:143]
	v_lshl_add_u32 v142, v178, 3, 0
	v_lshl_add_u32 v143, v179, 3, 0
	v_lshl_add_u64 v[198:199], s[14:15], 0, v[148:149]
	v_lshl_add_u32 v178, v182, 3, 0
	ds_read_b64 v[184:185], v129 offset:8192
	ds_read_b64 v[180:181], v142 offset:8192
	ds_read_b64 v[148:149], v143 offset:8192
	ds_read_b64 v[142:143], v178 offset:8192
	v_lshl_add_u64 v[144:145], s[14:15], 0, v[144:145]
	s_waitcnt lgkmcnt(3)
	v_pk_add_f32 v[146:147], v[146:147], v[184:185] op_sel_hi:[1,0] neg_lo:[0,1] neg_hi:[0,1]
	v_pk_add_f32 v[126:127], v[126:127], v[184:185] op_sel_hi:[1,0] neg_lo:[0,1] neg_hi:[0,1]
	v_pk_add_f32 v[124:125], v[124:125], v[184:185] op_sel_hi:[1,0] neg_lo:[0,1] neg_hi:[0,1]
	v_pk_add_f32 v[122:123], v[122:123], v[184:185] op_sel_hi:[1,0] neg_lo:[0,1] neg_hi:[0,1]
	s_waitcnt lgkmcnt(2)
	v_pk_add_f32 v[106:107], v[106:107], v[180:181] op_sel_hi:[1,0] neg_lo:[0,1] neg_hi:[0,1]
	v_pk_add_f32 v[114:115], v[114:115], v[180:181] op_sel_hi:[1,0] neg_lo:[0,1] neg_hi:[0,1]
	v_pk_add_f32 v[110:111], v[110:111], v[180:181] op_sel_hi:[1,0] neg_lo:[0,1] neg_hi:[0,1]
	v_pk_add_f32 v[108:109], v[108:109], v[180:181] op_sel_hi:[1,0] neg_lo:[0,1] neg_hi:[0,1]
	s_waitcnt lgkmcnt(1)
	v_pk_add_f32 v[150:151], v[150:151], v[148:149] op_sel_hi:[1,0] neg_lo:[0,1] neg_hi:[0,1]
	v_pk_add_f32 v[94:95], v[94:95], v[148:149] op_sel_hi:[1,0] neg_lo:[0,1] neg_hi:[0,1]
	v_pk_add_f32 v[92:93], v[92:93], v[148:149] op_sel_hi:[1,0] neg_lo:[0,1] neg_hi:[0,1]
	v_pk_add_f32 v[90:91], v[90:91], v[148:149] op_sel_hi:[1,0] neg_lo:[0,1] neg_hi:[0,1]
	s_waitcnt lgkmcnt(0)
	v_pk_add_f32 v[78:79], v[78:79], v[142:143] op_sel_hi:[1,0] neg_lo:[0,1] neg_hi:[0,1]
	v_pk_add_f32 v[76:77], v[76:77], v[142:143] op_sel_hi:[1,0] neg_lo:[0,1] neg_hi:[0,1]
	v_pk_mul_f32 v[146:147], v[184:185], v[146:147] op_sel:[1,0]
	v_pk_mul_f32 v[126:127], v[184:185], v[126:127] op_sel:[1,0]
	v_pk_mul_f32 v[124:125], v[184:185], v[124:125] op_sel:[1,0]
	v_pk_mul_f32 v[122:123], v[184:185], v[122:123] op_sel:[1,0]
	v_pk_mul_f32 v[106:107], v[180:181], v[106:107] op_sel:[1,0]
	v_pk_add_f32 v[74:75], v[74:75], v[142:143] op_sel_hi:[1,0] neg_lo:[0,1] neg_hi:[0,1]
	v_lshlrev_b64 v[192:193], 1, v[192:193]
	v_pk_mul_f32 v[114:115], v[180:181], v[114:115] op_sel:[1,0]
	v_pk_mul_f32 v[110:111], v[180:181], v[110:111] op_sel:[1,0]
	v_pk_mul_f32 v[108:109], v[180:181], v[108:109] op_sel:[1,0]
	v_pk_mul_f32 v[150:151], v[148:149], v[150:151] op_sel:[1,0]
	v_pk_mul_f32 v[94:95], v[148:149], v[94:95] op_sel:[1,0]
	v_pk_mul_f32 v[92:93], v[148:149], v[92:93] op_sel:[1,0]
	v_pk_mul_f32 v[90:91], v[148:149], v[90:91] op_sel:[1,0]
	v_pk_mul_f32 v[78:79], v[142:143], v[78:79] op_sel:[1,0]
	v_pk_mul_f32 v[76:77], v[142:143], v[76:77] op_sel:[1,0]
	v_pk_mul_f32 v[74:75], v[142:143], v[74:75] op_sel:[1,0]
	v_lshl_add_u64 v[182:183], v[196:197], 0, v[192:193]
	v_lshl_add_u64 v[178:179], v[144:145], 0, v[192:193]
	v_lshl_add_u64 v[144:145], v[198:199], 0, v[192:193]
	v_pk_add_f32 v[152:153], v[152:153], v[142:143] op_sel_hi:[1,0] neg_lo:[0,1] neg_hi:[0,1]
	s_waitcnt vmcnt(1)
	v_pk_fma_f32 v[146:147], v[4:5], v[146:147], v[12:13]
	s_waitcnt vmcnt(0)
	v_pk_fma_f32 v[126:127], v[0:1], v[126:127], v[8:9]
	v_pk_fma_f32 v[124:125], v[6:7], v[124:125], v[14:15]
	v_pk_fma_f32 v[122:123], v[2:3], v[122:123], v[10:11]
	v_pk_fma_f32 v[106:107], v[2:3], v[106:107], v[10:11]
	v_pk_fma_f32 v[114:115], v[4:5], v[114:115], v[12:13]
	v_pk_fma_f32 v[110:111], v[0:1], v[110:111], v[8:9]
	v_pk_fma_f32 v[108:109], v[6:7], v[108:109], v[14:15]
	v_pk_fma_f32 v[150:151], v[4:5], v[150:151], v[12:13]
	v_pk_fma_f32 v[94:95], v[0:1], v[94:95], v[8:9]
	v_pk_fma_f32 v[196:197], v[6:7], v[92:93], v[14:15]
	v_pk_fma_f32 v[198:199], v[2:3], v[90:91], v[10:11]
	v_pk_fma_f32 v[200:201], v[0:1], v[78:79], v[8:9]
	v_pk_fma_f32 v[202:203], v[6:7], v[76:77], v[14:15]
	v_cvt_pk_bf16_f32 v76, v146, v147
	v_cvt_pk_bf16_f32 v77, v124, v125
	v_cvt_pk_bf16_f32 v78, v126, v127
	v_cvt_pk_bf16_f32 v79, v122, v123
	v_cvt_pk_bf16_f32 v93, v106, v107
	v_pk_fma_f32 v[74:75], v[2:3], v[74:75], v[10:11]
	v_cvt_pk_bf16_f32 v90, v114, v115
	v_cvt_pk_bf16_f32 v91, v108, v109
	v_cvt_pk_bf16_f32 v92, v110, v111
	v_cvt_pk_bf16_f32 v106, v150, v151
	v_cvt_pk_bf16_f32 v107, v196, v197
	v_cvt_pk_bf16_f32 v108, v94, v95
	v_cvt_pk_bf16_f32 v109, v198, v199
	global_store_dwordx4 v[182:183], v[76:79], off
	global_store_dwordx4 v[178:179], v[90:93], off
	global_store_dwordx4 v[144:145], v[106:109], off
	v_pk_mul_f32 v[152:153], v[142:143], v[152:153] op_sel:[1,0]
	v_cvt_pk_bf16_f32 v93, v74, v75
	v_lshl_add_u64 v[74:75], s[14:15], 0, v[98:99]
	v_lshl_add_u64 v[76:77], v[74:75], 0, v[192:193]
	v_lshl_add_u32 v74, v188, 3, 0
	ds_read_b64 v[74:75], v74 offset:8192
	v_pk_fma_f32 v[152:153], v[4:5], v[152:153], v[12:13]
	v_cvt_pk_bf16_f32 v91, v202, v203
	v_cvt_pk_bf16_f32 v90, v152, v153
	v_cvt_pk_bf16_f32 v92, v200, v201
	global_store_dwordx4 v[76:77], v[90:93], off
	v_lshl_add_u32 v78, v189, 3, 0
	s_waitcnt lgkmcnt(0)
; __device__ __forceinline__ unsigned pk2(float lo, float hi) { f32x2_t v = {lo, hi}; bf16x2_t b = __builtin_convertvector(v, bf16x2_t); return __builtin_bit_cast(unsigned, b); }
;     __device__ __forceinline__ void fused(f32x4 (&acc)[2][2][4][2], const Unit& u, int wr, int wc, int fr, int fq, PG8_LAS unsigned char* lds, int wid, int lane) const {
;     ...
; #pragma unroll
;         for (int bj = 0; bj < 2; ++bj) {
;             const int col = u.pn * 256 + bj * 128 + wc * 32 + fq * 8;
;             float gg[8], bb[8]; ld8f32(gam + col, gg); ld8f32(bet + col, bb);
; #pragma unroll
;             for (int ai = 0; ai < 2; ++ai)
; #pragma unroll
;                 for (int m = 0; m < 4; ++m) {
;                     const int rl = ai * 128 + wr * 64 + m * 16 + fr;
;                     const float mu = S[rl * 2], rs = S[rl * 2 + 1];
;                     const f32x4 v0 = acc[ai][bj][m][0], v1 = acc[ai][bj][m][1];
;                     float y[8];
; #pragma unroll
;                     for (int j = 0; j < 4; ++j) { y[j] = (v0[j] - mu) * rs * gg[j] + bb[j]; y[4 + j] = (v1[j] - mu) * rs * gg[4 + j] + bb[4 + j]; }
;                     const size_t off = (size_t)(u.pm * 256 + rl) * 1024 + col;
;                     if (of32) { *(float4*)(of32 + off) = make_float4(y[0], y[1], y[2], y[3]); *(float4*)(of32 + off + 4) = make_float4(y[4], y[5], y[6], y[7]); }
;                     if (obf) { uint4 o; o.x = pk2(y[0], y[1]); o.y = pk2(y[2], y[3]); o.z = pk2(y[4], y[5]); o.w = pk2(y[6], y[7]); *(uint4*)(obf + off) = o; }
;                 }
;         }
	v_pk_add_f32 v[62:63], v[62:63], v[74:75] op_sel_hi:[1,0] neg_lo:[0,1] neg_hi:[0,1]
	v_lshl_add_u32 v90, v190, 3, 0
	v_lshl_add_u32 v92, v191, 3, 0
	ds_read_b64 v[78:79], v78 offset:8192
	ds_read_b64 v[90:91], v90 offset:8192
	ds_read_b64 v[92:93], v92 offset:8192
	v_pk_add_f32 v[60:61], v[60:61], v[74:75] op_sel_hi:[1,0] neg_lo:[0,1] neg_hi:[0,1]
	v_pk_add_f32 v[94:95], v[154:155], v[74:75] op_sel_hi:[1,0] neg_lo:[0,1] neg_hi:[0,1]
	v_pk_mul_f32 v[62:63], v[74:75], v[62:63] op_sel:[1,0]
	v_pk_mul_f32 v[60:61], v[74:75], v[60:61] op_sel:[1,0]
	v_pk_add_f32 v[58:59], v[58:59], v[74:75] op_sel_hi:[1,0] neg_lo:[0,1] neg_hi:[0,1]
	v_pk_mul_f32 v[94:95], v[74:75], v[94:95] op_sel:[1,0]
	v_pk_fma_f32 v[62:63], v[0:1], v[62:63], v[8:9]
	v_pk_fma_f32 v[60:61], v[6:7], v[60:61], v[14:15]
	v_pk_mul_f32 v[58:59], v[74:75], v[58:59] op_sel:[1,0]
	s_waitcnt lgkmcnt(2)
	v_pk_add_f32 v[46:47], v[46:47], v[78:79] op_sel_hi:[1,0] neg_lo:[0,1] neg_hi:[0,1]
	v_pk_add_f32 v[44:45], v[44:45], v[78:79] op_sel_hi:[1,0] neg_lo:[0,1] neg_hi:[0,1]
	v_pk_fma_f32 v[94:95], v[4:5], v[94:95], v[12:13]
	v_pk_fma_f32 v[98:99], v[2:3], v[58:59], v[10:11]
	v_cvt_pk_bf16_f32 v59, v60, v61
	v_cvt_pk_bf16_f32 v60, v62, v63
	v_lshl_add_u64 v[62:63], s[14:15], 0, v[82:83]
	v_pk_add_f32 v[50:51], v[50:51], v[78:79] op_sel_hi:[1,0] neg_lo:[0,1] neg_hi:[0,1]
	v_pk_mul_f32 v[46:47], v[78:79], v[46:47] op_sel:[1,0]
	v_pk_mul_f32 v[44:45], v[78:79], v[44:45] op_sel:[1,0]
	v_pk_add_f32 v[42:43], v[42:43], v[78:79] op_sel_hi:[1,0] neg_lo:[0,1] neg_hi:[0,1]
	v_cvt_pk_bf16_f32 v58, v94, v95
	v_cvt_pk_bf16_f32 v61, v98, v99
	v_lshl_add_u64 v[62:63], v[62:63], 0, v[192:193]
	v_pk_mul_f32 v[50:51], v[78:79], v[50:51] op_sel:[1,0]
	v_pk_fma_f32 v[46:47], v[0:1], v[46:47], v[8:9]
	v_pk_fma_f32 v[44:45], v[6:7], v[44:45], v[14:15]
	v_pk_mul_f32 v[42:43], v[78:79], v[42:43] op_sel:[1,0]
	global_store_dwordx4 v[62:63], v[58:61], off
	v_pk_fma_f32 v[50:51], v[4:5], v[50:51], v[12:13]
	s_waitcnt lgkmcnt(1)
	v_pk_add_f32 v[22:23], v[22:23], v[90:91] op_sel_hi:[1,0] neg_lo:[0,1] neg_hi:[0,1]
	v_pk_fma_f32 v[58:59], v[2:3], v[42:43], v[10:11]
	v_cvt_pk_bf16_f32 v43, v44, v45
	v_cvt_pk_bf16_f32 v44, v46, v47
	v_lshl_add_u64 v[46:47], s[14:15], 0, v[66:67]
	v_cvt_pk_bf16_f32 v42, v50, v51
	v_cvt_pk_bf16_f32 v45, v58, v59
	v_lshl_add_u64 v[46:47], v[46:47], 0, v[192:193]
	global_store_dwordx4 v[46:47], v[42:45], off
	v_pk_add_f32 v[50:51], v[158:159], v[90:91] op_sel_hi:[1,0] neg_lo:[0,1] neg_hi:[0,1]
	v_pk_add_f32 v[58:59], v[162:163], v[90:91] op_sel_hi:[1,0] neg_lo:[0,1] neg_hi:[0,1]
	v_pk_add_f32 v[42:43], v[160:161], v[90:91] op_sel_hi:[1,0] neg_lo:[0,1] neg_hi:[0,1]
	v_pk_add_f32 v[44:45], v[164:165], v[90:91] op_sel_hi:[1,0] neg_lo:[0,1] neg_hi:[0,1]
	v_pk_mul_f32 v[42:43], v[90:91], v[42:43] op_sel:[1,0]
	v_pk_mul_f32 v[50:51], v[90:91], v[50:51] op_sel:[1,0]
	v_pk_fma_f32 v[42:43], v[4:5], v[42:43], v[12:13]
	v_pk_mul_f32 v[44:45], v[90:91], v[44:45] op_sel:[1,0]
	v_pk_fma_f32 v[50:51], v[6:7], v[50:51], v[14:15]
	v_pk_mul_f32 v[58:59], v[90:91], v[58:59] op_sel:[1,0]
	v_pk_fma_f32 v[44:45], v[0:1], v[44:45], v[8:9]
	v_pk_fma_f32 v[58:59], v[2:3], v[58:59], v[10:11]
	v_cvt_pk_bf16_f32 v42, v42, v43
	v_cvt_pk_bf16_f32 v43, v50, v51
	v_lshl_add_u64 v[50:51], s[14:15], 0, v[156:157]
	v_cvt_pk_bf16_f32 v44, v44, v45
	v_cvt_pk_bf16_f32 v45, v58, v59
	v_lshl_add_u64 v[50:51], v[50:51], 0, v[192:193]
	global_store_dwordx4 v[50:51], v[42:45], off
	v_pk_add_f32 v[16:17], v[16:17], v[90:91] op_sel_hi:[1,0] neg_lo:[0,1] neg_hi:[0,1]
	v_pk_mul_f32 v[22:23], v[90:91], v[22:23] op_sel:[1,0]
	s_waitcnt lgkmcnt(0)
	v_pk_add_f32 v[42:43], v[170:171], v[92:93] op_sel_hi:[1,0] neg_lo:[0,1] neg_hi:[0,1]
	v_pk_mul_f32 v[16:17], v[90:91], v[16:17] op_sel:[1,0]
	v_pk_mul_f32 v[42:43], v[92:93], v[42:43] op_sel:[1,0]
	v_pk_add_f32 v[24:25], v[24:25], v[90:91] op_sel_hi:[1,0] neg_lo:[0,1] neg_hi:[0,1]
	v_pk_fma_f32 v[4:5], v[4:5], v[42:43], v[12:13]
	v_pk_add_f32 v[12:13], v[174:175], v[92:93] op_sel_hi:[1,0] neg_lo:[0,1] neg_hi:[0,1]
	v_pk_add_f32 v[42:43], v[118:119], v[184:185] op_sel_hi:[1,0] neg_lo:[0,1] neg_hi:[0,1]
	v_pk_mul_f32 v[12:13], v[92:93], v[12:13] op_sel:[1,0]
	v_pk_mul_f32 v[42:43], v[184:185], v[42:43] op_sel:[1,0]
	v_pk_fma_f32 v[8:9], v[0:1], v[12:13], v[8:9]
	v_pk_add_f32 v[0:1], v[166:167], v[92:93] op_sel_hi:[1,0] neg_lo:[0,1] neg_hi:[0,1]
	v_pk_mul_f32 v[24:25], v[90:91], v[24:25] op_sel:[1,0]
	v_pk_mul_f32 v[0:1], v[92:93], v[0:1] op_sel:[1,0]
	v_pk_add_f32 v[38:39], v[38:39], v[78:79] op_sel_hi:[1,0] neg_lo:[0,1] neg_hi:[0,1]
	v_pk_fma_f32 v[6:7], v[6:7], v[0:1], v[14:15]
	v_pk_add_f32 v[0:1], v[168:169], v[92:93] op_sel_hi:[1,0] neg_lo:[0,1] neg_hi:[0,1]
	v_pk_add_f32 v[36:37], v[36:37], v[78:79] op_sel_hi:[1,0] neg_lo:[0,1] neg_hi:[0,1]
	v_pk_mul_f32 v[0:1], v[92:93], v[0:1] op_sel:[1,0]
	v_pk_add_f32 v[32:33], v[32:33], v[78:79] op_sel_hi:[1,0] neg_lo:[0,1] neg_hi:[0,1]
	v_pk_fma_f32 v[10:11], v[2:3], v[0:1], v[10:11]
	v_cvt_pk_bf16_f32 v0, v4, v5
	v_lshl_add_u64 v[4:5], s[14:15], 0, v[34:35]
	v_cvt_pk_bf16_f32 v1, v6, v7
	v_cvt_pk_bf16_f32 v2, v8, v9
	v_cvt_pk_bf16_f32 v3, v10, v11
	v_lshl_add_u64 v[58:59], v[4:5], 0, v[192:193]
	global_store_dwordx4 v[58:59], v[0:3], off
	s_nop 1
	v_mov_b64_e32 v[0:1], v[204:205]
	v_mov_b64_e32 v[2:3], v[206:207]
	s_nop 0
	v_mov_b64_e32 v[4:5], v[208:209]
	v_mov_b64_e32 v[6:7], v[210:211]
	v_mov_b64_e32 v[8:9], v[212:213]
	v_mov_b64_e32 v[10:11], v[214:215]
	v_mov_b64_e32 v[12:13], v[216:217]
	v_mov_b64_e32 v[14:15], v[218:219]
	v_pk_add_f32 v[34:35], v[120:121], v[184:185] op_sel_hi:[1,0] neg_lo:[0,1] neg_hi:[0,1]
	v_pk_mul_f32 v[38:39], v[78:79], v[38:39] op_sel:[1,0]
; __device__ __forceinline__ unsigned pk2(float lo, float hi) { f32x2_t v = {lo, hi}; bf16x2_t b = __builtin_convertvector(v, bf16x2_t); return __builtin_bit_cast(unsigned, b); }
;     __device__ __forceinline__ void fused(f32x4 (&acc)[2][2][4][2], const Unit& u, int wr, int wc, int fr, int fq, PG8_LAS unsigned char* lds, int wid, int lane) const {
;     ...
; #pragma unroll
;         for (int bj = 0; bj < 2; ++bj) {
;             const int col = u.pn * 256 + bj * 128 + wc * 32 + fq * 8;
;             float gg[8], bb[8]; ld8f32(gam + col, gg); ld8f32(bet + col, bb);
; #pragma unroll
;             for (int ai = 0; ai < 2; ++ai)
; #pragma unroll
;                 for (int m = 0; m < 4; ++m) {
;                     const int rl = ai * 128 + wr * 64 + m * 16 + fr;
;                     const float mu = S[rl * 2], rs = S[rl * 2 + 1];
;                     const f32x4 v0 = acc[ai][bj][m][0], v1 = acc[ai][bj][m][1];
;                     float y[8];
; #pragma unroll
;                     for (int j = 0; j < 4; ++j) { y[j] = (v0[j] - mu) * rs * gg[j] + bb[j]; y[4 + j] = (v1[j] - mu) * rs * gg[4 + j] + bb[4 + j]; }
;                     const size_t off = (size_t)(u.pm * 256 + rl) * 1024 + col;
;                     if (of32) { *(float4*)(of32 + off) = make_float4(y[0], y[1], y[2], y[3]); *(float4*)(of32 + off + 4) = make_float4(y[4], y[5], y[6], y[7]); }
;                     if (obf) { uint4 o; o.x = pk2(y[0], y[1]); o.y = pk2(y[2], y[3]); o.z = pk2(y[4], y[5]); o.w = pk2(y[6], y[7]); *(uint4*)(obf + off) = o; }
;                 }
;         }
	v_pk_mul_f32 v[34:35], v[184:185], v[34:35] op_sel:[1,0]
	v_pk_mul_f32 v[36:37], v[78:79], v[36:37] op_sel:[1,0]
	v_pk_mul_f32 v[32:33], v[78:79], v[32:33] op_sel:[1,0]
	v_pk_add_f32 v[20:21], v[20:21], v[90:91] op_sel_hi:[1,0] neg_lo:[0,1] neg_hi:[0,1]
	v_pk_fma_f32 v[34:35], v[34:35], v[4:5], v[0:1]
	v_pk_fma_f32 v[24:25], v[24:25], v[4:5], v[0:1]
	v_pk_fma_f32 v[44:45], v[42:43], v[8:9], v[12:13]
	v_pk_add_f32 v[42:43], v[116:117], v[184:185] op_sel_hi:[1,0] neg_lo:[0,1] neg_hi:[0,1]
	v_cvt_pk_bf16_f32 v44, v44, v45
	v_pk_mul_f32 v[42:43], v[184:185], v[42:43] op_sel:[1,0]
	v_pk_fma_f32 v[22:23], v[22:23], v[8:9], v[12:13]
	v_pk_fma_f32 v[60:61], v[42:43], v[6:7], v[2:3]
	v_pk_add_f32 v[42:43], v[112:113], v[184:185] op_sel_hi:[1,0] neg_lo:[0,1] neg_hi:[0,1]
	v_pk_fma_f32 v[16:17], v[16:17], v[10:11], v[14:15]
	v_pk_mul_f32 v[42:43], v[184:185], v[42:43] op_sel:[1,0]
	v_cvt_pk_bf16_f32 v22, v22, v23
	v_pk_fma_f32 v[66:67], v[42:43], v[10:11], v[14:15]
	v_cvt_pk_bf16_f32 v42, v34, v35
	v_cvt_pk_bf16_f32 v43, v60, v61
	v_cvt_pk_bf16_f32 v45, v66, v67
	global_store_dwordx4 v[182:183], v[42:45], off offset:256
	v_pk_add_f32 v[34:35], v[100:101], v[180:181] op_sel_hi:[1,0] neg_lo:[0,1] neg_hi:[0,1]
	v_cvt_pk_bf16_f32 v23, v16, v17
	v_pk_add_f32 v[42:43], v[104:105], v[180:181] op_sel_hi:[1,0] neg_lo:[0,1] neg_hi:[0,1]
	v_pk_mul_f32 v[34:35], v[180:181], v[34:35] op_sel:[1,0]
	v_pk_mul_f32 v[42:43], v[180:181], v[42:43] op_sel:[1,0]
	v_pk_fma_f32 v[34:35], v[34:35], v[4:5], v[0:1]
	v_pk_fma_f32 v[44:45], v[42:43], v[8:9], v[12:13]
	v_pk_add_f32 v[42:43], v[102:103], v[180:181] op_sel_hi:[1,0] neg_lo:[0,1] neg_hi:[0,1]
	v_cvt_pk_bf16_f32 v44, v44, v45
	v_pk_mul_f32 v[42:43], v[180:181], v[42:43] op_sel:[1,0]
	v_pk_add_f32 v[16:17], v[26:27], v[92:93] op_sel_hi:[1,0] neg_lo:[0,1] neg_hi:[0,1]
	v_pk_fma_f32 v[60:61], v[42:43], v[6:7], v[2:3]
	v_pk_add_f32 v[42:43], v[96:97], v[180:181] op_sel_hi:[1,0] neg_lo:[0,1] neg_hi:[0,1]
	v_pk_mul_f32 v[16:17], v[92:93], v[16:17] op_sel:[1,0]
	v_pk_mul_f32 v[42:43], v[180:181], v[42:43] op_sel:[1,0]
	v_pk_fma_f32 v[38:39], v[38:39], v[8:9], v[12:13]
	v_pk_fma_f32 v[66:67], v[42:43], v[10:11], v[14:15]
	v_cvt_pk_bf16_f32 v42, v34, v35
	v_cvt_pk_bf16_f32 v43, v60, v61
	v_cvt_pk_bf16_f32 v45, v66, v67
	global_store_dwordx4 v[178:179], v[42:45], off offset:256
	v_pk_add_f32 v[34:35], v[84:85], v[148:149] op_sel_hi:[1,0] neg_lo:[0,1] neg_hi:[0,1]
	v_pk_fma_f32 v[36:37], v[36:37], v[6:7], v[2:3]
	v_pk_add_f32 v[42:43], v[88:89], v[148:149] op_sel_hi:[1,0] neg_lo:[0,1] neg_hi:[0,1]
	v_pk_mul_f32 v[34:35], v[148:149], v[34:35] op_sel:[1,0]
	v_pk_mul_f32 v[42:43], v[148:149], v[42:43] op_sel:[1,0]
	v_pk_fma_f32 v[34:35], v[34:35], v[4:5], v[0:1]
	v_pk_fma_f32 v[44:45], v[42:43], v[8:9], v[12:13]
	v_pk_add_f32 v[42:43], v[86:87], v[148:149] op_sel_hi:[1,0] neg_lo:[0,1] neg_hi:[0,1]
	v_cvt_pk_bf16_f32 v44, v44, v45
	v_pk_mul_f32 v[42:43], v[148:149], v[42:43] op_sel:[1,0]
	v_pk_mul_f32 v[20:21], v[90:91], v[20:21] op_sel:[1,0]
	v_pk_fma_f32 v[60:61], v[42:43], v[6:7], v[2:3]
	v_pk_add_f32 v[42:43], v[80:81], v[148:149] op_sel_hi:[1,0] neg_lo:[0,1] neg_hi:[0,1]
	s_nop 0
	v_pk_mul_f32 v[42:43], v[148:149], v[42:43] op_sel:[1,0]
	s_nop 0
	v_pk_fma_f32 v[66:67], v[42:43], v[10:11], v[14:15]
	v_cvt_pk_bf16_f32 v42, v34, v35
	v_cvt_pk_bf16_f32 v43, v60, v61
	v_cvt_pk_bf16_f32 v45, v66, v67
	global_store_dwordx4 v[144:145], v[42:45], off offset:256
	v_pk_add_f32 v[34:35], v[68:69], v[142:143] op_sel_hi:[1,0] neg_lo:[0,1] neg_hi:[0,1]
	s_nop 0
	v_pk_add_f32 v[42:43], v[72:73], v[142:143] op_sel_hi:[1,0] neg_lo:[0,1] neg_hi:[0,1]
	v_pk_mul_f32 v[34:35], v[142:143], v[34:35] op_sel:[1,0]
	v_pk_mul_f32 v[42:43], v[142:143], v[42:43] op_sel:[1,0]
	v_pk_fma_f32 v[34:35], v[34:35], v[4:5], v[0:1]
	v_pk_fma_f32 v[44:45], v[42:43], v[8:9], v[12:13]
	v_pk_add_f32 v[42:43], v[70:71], v[142:143] op_sel_hi:[1,0] neg_lo:[0,1] neg_hi:[0,1]
	v_cvt_pk_bf16_f32 v44, v44, v45
	v_pk_mul_f32 v[42:43], v[142:143], v[42:43] op_sel:[1,0]
	s_nop 0
	v_pk_fma_f32 v[60:61], v[42:43], v[6:7], v[2:3]
	v_pk_add_f32 v[42:43], v[64:65], v[142:143] op_sel_hi:[1,0] neg_lo:[0,1] neg_hi:[0,1]
	s_nop 0
	v_pk_mul_f32 v[42:43], v[142:143], v[42:43] op_sel:[1,0]
	s_nop 0
	v_pk_fma_f32 v[64:65], v[42:43], v[10:11], v[14:15]
	v_cvt_pk_bf16_f32 v42, v34, v35
	v_cvt_pk_bf16_f32 v43, v60, v61
	v_cvt_pk_bf16_f32 v45, v64, v65
	global_store_dwordx4 v[76:77], v[42:45], off offset:256
	v_pk_add_f32 v[34:35], v[52:53], v[74:75] op_sel_hi:[1,0] neg_lo:[0,1] neg_hi:[0,1]
	s_nop 0
	v_pk_add_f32 v[42:43], v[56:57], v[74:75] op_sel_hi:[1,0] neg_lo:[0,1] neg_hi:[0,1]
	v_pk_mul_f32 v[34:35], v[74:75], v[34:35] op_sel:[1,0]
	v_pk_mul_f32 v[42:43], v[74:75], v[42:43] op_sel:[1,0]
	v_pk_fma_f32 v[34:35], v[34:35], v[4:5], v[0:1]
	v_pk_fma_f32 v[44:45], v[42:43], v[8:9], v[12:13]
	v_pk_add_f32 v[42:43], v[54:55], v[74:75] op_sel_hi:[1,0] neg_lo:[0,1] neg_hi:[0,1]
	v_cvt_pk_bf16_f32 v44, v44, v45
	v_pk_mul_f32 v[42:43], v[74:75], v[42:43] op_sel:[1,0]
	s_nop 0
	v_pk_fma_f32 v[52:53], v[42:43], v[6:7], v[2:3]
	v_pk_add_f32 v[42:43], v[48:49], v[74:75] op_sel_hi:[1,0] neg_lo:[0,1] neg_hi:[0,1]
	s_nop 0
	v_pk_mul_f32 v[42:43], v[74:75], v[42:43] op_sel:[1,0]
	s_nop 0
	v_pk_fma_f32 v[48:49], v[42:43], v[10:11], v[14:15]
	v_cvt_pk_bf16_f32 v42, v34, v35
	v_pk_add_f32 v[34:35], v[40:41], v[78:79] op_sel_hi:[1,0] neg_lo:[0,1] neg_hi:[0,1]
	v_pk_fma_f32 v[40:41], v[32:33], v[10:11], v[14:15]
	v_pk_mul_f32 v[34:35], v[78:79], v[34:35] op_sel:[1,0]
	v_cvt_pk_bf16_f32 v33, v36, v37
	v_pk_fma_f32 v[34:35], v[34:35], v[4:5], v[0:1]
	v_pk_fma_f32 v[0:1], v[16:17], v[4:5], v[0:1]
	v_pk_add_f32 v[4:5], v[30:31], v[92:93] op_sel_hi:[1,0] neg_lo:[0,1] neg_hi:[0,1]
	v_cvt_pk_bf16_f32 v32, v34, v35
	v_pk_mul_f32 v[4:5], v[92:93], v[4:5] op_sel:[1,0]
	v_cvt_pk_bf16_f32 v34, v38, v39
	v_pk_fma_f32 v[4:5], v[4:5], v[8:9], v[12:13]
	v_pk_add_f32 v[8:9], v[18:19], v[92:93] op_sel_hi:[1,0] neg_lo:[0,1] neg_hi:[0,1]
	v_cvt_pk_bf16_f32 v35, v40, v41
	v_pk_mul_f32 v[8:9], v[92:93], v[8:9] op_sel:[1,0]
	global_store_dwordx4 v[46:47], v[32:35], off offset:256
	v_cvt_pk_bf16_f32 v43, v52, v53
	v_cvt_pk_bf16_f32 v45, v48, v49
	v_pk_fma_f32 v[32:33], v[20:21], v[6:7], v[2:3]
	v_pk_fma_f32 v[2:3], v[8:9], v[6:7], v[2:3]
	v_pk_add_f32 v[6:7], v[28:29], v[92:93] op_sel_hi:[1,0] neg_lo:[0,1] neg_hi:[0,1]
	v_cvt_pk_bf16_f32 v20, v24, v25
	v_pk_mul_f32 v[6:7], v[92:93], v[6:7] op_sel:[1,0]
	v_cvt_pk_bf16_f32 v21, v32, v33
	v_pk_fma_f32 v[6:7], v[6:7], v[10:11], v[14:15]
	v_cvt_pk_bf16_f32 v0, v0, v1
	v_cvt_pk_bf16_f32 v1, v2, v3
	v_cvt_pk_bf16_f32 v2, v4, v5
	v_cvt_pk_bf16_f32 v3, v6, v7
	global_store_dwordx4 v[62:63], v[42:45], off offset:256
	global_store_dwordx4 v[50:51], v[20:23], off offset:256
	global_store_dwordx4 v[58:59], v[0:3], off offset:256

; __device__ __forceinline__ unsigned pk2(float lo, float hi) { f32x2_t v = {lo, hi}; bf16x2_t b = __builtin_convertvector(v, bf16x2_t); return __builtin_bit_cast(unsigned, b); }
;     __device__ __forceinline__ void fused(f32x4 (&acc)[2][2][4][2], const Unit& u, int wr, int wc, int fr, int fq, PG8_LAS unsigned char* lds, int wid, int lane) const {
;     ...
; #pragma unroll
;         for (int bj = 0; bj < 2; ++bj) {
;             const int col = u.pn * 256 + bj * 128 + wc * 32 + fq * 8;
;             float gg[8], bb[8]; ld8f32(gam + col, gg); ld8f32(bet + col, bb);
; #pragma unroll
;             for (int ai = 0; ai < 2; ++ai)
; #pragma unroll
;                 for (int m = 0; m < 4; ++m) {
;                     const int rl = ai * 128 + wr * 64 + m * 16 + fr;
;                     const float mu = S[rl * 2], rs = S[rl * 2 + 1];
;                     const f32x4 v0 = acc[ai][bj][m][0], v1 = acc[ai][bj][m][1];
;                     float y[8];
; #pragma unroll
;                     for (int j = 0; j < 4; ++j) { y[j] = (v0[j] - mu) * rs * gg[j] + bb[j]; y[4 + j] = (v1[j] - mu) * rs * gg[4 + j] + bb[4 + j]; }
;                     const size_t off = (size_t)(u.pm * 256 + rl) * 1024 + col;
;                     if (of32) { *(float4*)(of32 + off) = make_float4(y[0], y[1], y[2], y[3]); *(float4*)(of32 + off + 4) = make_float4(y[4], y[5], y[6], y[7]); }
;                     if (obf) { uint4 o; o.x = pk2(y[0], y[1]); o.y = pk2(y[2], y[3]); o.z = pk2(y[4], y[5]); o.w = pk2(y[6], y[7]); *(uint4*)(obf + off) = o; }
;                 }
;         }
.LBB0_1276:
	s_or_b64 exec, exec, s[14:15]
	s_cmp_eq_u64 s[0:1], 0
	s_waitcnt lgkmcnt(0)
	s_barrier
	s_cbranch_scc1 .LBB0_1278
	v_or_b32_e32 v10, s9, v128
	v_or_b32_e32 v10, s8, v10
	v_ashrrev_i32_e32 v11, 31, v10
	v_lshlrev_b64 v[10:11], 2, v[10:11]
	v_lshl_add_u64 v[150:151], s[4:5], 0, v[10:11]
	v_lshl_add_u64 v[148:149], s[16:17], 0, v[10:11]
	global_load_dwordx4 v[162:165], v[150:151], off
	global_load_dwordx4 v[166:169], v[148:149], off
	global_load_dwordx4 v[174:177], v[148:149], off offset:16
	global_load_dwordx4 v[178:181], v[150:151], off offset:16
	global_load_dwordx4 v[200:203], v[150:151], off offset:512
	global_load_dwordx4 v[204:207], v[148:149], off offset:512
	global_load_dwordx4 v[208:211], v[148:149], off offset:528
	global_load_dwordx4 v[212:215], v[150:151], off offset:528
	v_lshl_add_u32 v161, v152, 3, 0
	v_lshlrev_b64 v[128:129], 12, v[130:131]
	v_lshl_add_u32 v173, v153, 3, 0
	v_lshlrev_b64 v[130:131], 12, v[132:133]
	v_lshlrev_b64 v[132:133], 12, v[136:137]
	v_lshlrev_b64 v[136:137], 12, v[138:139]
	v_lshl_add_u32 v138, v157, 3, 0
	v_lshl_add_u32 v186, v158, 3, 0
	v_lshl_add_u32 v182, v154, 3, 0
	v_lshl_add_u32 v183, v155, 3, 0
	v_lshlrev_b64 v[152:153], 12, v[142:143]
	v_lshl_add_u32 v187, v159, 3, 0
	v_lshl_add_u32 v188, v160, 3, 0
	v_lshlrev_b64 v[156:157], 12, v[146:147]
	ds_read_b64 v[158:159], v161 offset:8192
	v_lshl_add_u64 v[160:161], s[0:1], 0, v[128:129]
	v_lshl_add_u64 v[170:171], s[0:1], 0, v[132:133]
	ds_read_b64 v[154:155], v173 offset:8192
	ds_read_b64 v[146:147], v182 offset:8192
	ds_read_b64 v[142:143], v183 offset:8192
	ds_read_b64 v[138:139], v138 offset:8192
	ds_read_b64 v[132:133], v186 offset:8192
	ds_read_b64 v[128:129], v187 offset:8192
	ds_read_b64 v[196:197], v188 offset:8192
	v_lshl_add_u64 v[182:183], s[0:1], 0, v[152:153]
	v_lshl_add_u64 v[152:153], v[170:171], 0, v[10:11]
	s_waitcnt lgkmcnt(6)
	v_pk_add_f32 v[108:109], v[108:109], v[154:155] op_sel_hi:[1,0] neg_lo:[0,1] neg_hi:[0,1]
	v_pk_add_f32 v[170:171], v[106:107], v[154:155] op_sel_hi:[1,0] neg_lo:[0,1] neg_hi:[0,1]
	s_waitcnt lgkmcnt(0)
	v_pk_add_f32 v[8:9], v[8:9], v[196:197] op_sel_hi:[1,0] neg_lo:[0,1] neg_hi:[0,1]
	v_lshlrev_b64 v[140:141], 12, v[140:141]
	v_pk_mul_f32 v[8:9], v[196:197], v[8:9] op_sel:[1,0]
	v_lshlrev_b64 v[144:145], 12, v[144:145]
	v_pk_add_f32 v[134:135], v[134:135], v[158:159] op_sel_hi:[1,0] neg_lo:[0,1] neg_hi:[0,1]
	v_pk_add_f32 v[126:127], v[126:127], v[158:159] op_sel_hi:[1,0] neg_lo:[0,1] neg_hi:[0,1]
	v_pk_mul_f32 v[190:191], v[154:155], v[108:109] op_sel:[1,0]
	v_lshl_add_u64 v[130:131], s[0:1], 0, v[130:131]
	v_lshl_add_u64 v[136:137], s[0:1], 0, v[136:137]
	v_lshl_add_u64 v[140:141], s[0:1], 0, v[140:141]
	v_lshl_add_u64 v[184:185], s[0:1], 0, v[144:145]
	v_lshl_add_u64 v[186:187], s[0:1], 0, v[156:157]
	v_pk_add_f32 v[12:13], v[12:13], v[196:197] op_sel_hi:[1,0] neg_lo:[0,1] neg_hi:[0,1]
	v_pk_add_f32 v[14:15], v[14:15], v[196:197] op_sel_hi:[1,0] neg_lo:[0,1] neg_hi:[0,1]
	v_pk_add_f32 v[124:125], v[124:125], v[158:159] op_sel_hi:[1,0] neg_lo:[0,1] neg_hi:[0,1]
	v_pk_add_f32 v[122:123], v[122:123], v[158:159] op_sel_hi:[1,0] neg_lo:[0,1] neg_hi:[0,1]
	v_pk_add_f32 v[114:115], v[114:115], v[154:155] op_sel_hi:[1,0] neg_lo:[0,1] neg_hi:[0,1]
	v_pk_add_f32 v[110:111], v[110:111], v[154:155] op_sel_hi:[1,0] neg_lo:[0,1] neg_hi:[0,1]
	v_pk_mul_f32 v[134:135], v[158:159], v[134:135] op_sel:[1,0]
	v_pk_mul_f32 v[126:127], v[158:159], v[126:127] op_sel:[1,0]
	v_lshl_add_u64 v[160:161], v[160:161], 0, v[10:11]
	v_lshl_add_u64 v[156:157], v[130:131], 0, v[10:11]
	v_lshl_add_u64 v[144:145], v[136:137], 0, v[10:11]
	v_lshl_add_u64 v[140:141], v[140:141], 0, v[10:11]
	v_lshl_add_u64 v[136:137], v[182:183], 0, v[10:11]
	v_lshl_add_u64 v[130:131], v[184:185], 0, v[10:11]
	v_lshl_add_u64 v[10:11], v[186:187], 0, v[10:11]
	v_pk_mul_f32 v[106:107], v[196:197], v[12:13] op_sel:[1,0]
	v_pk_mul_f32 v[182:183], v[196:197], v[14:15] op_sel:[1,0]
	v_pk_mul_f32 v[184:185], v[158:159], v[124:125] op_sel:[1,0]
	v_pk_mul_f32 v[186:187], v[158:159], v[122:123] op_sel:[1,0]
	v_pk_mul_f32 v[114:115], v[154:155], v[114:115] op_sel:[1,0]
	v_pk_mul_f32 v[110:111], v[154:155], v[110:111] op_sel:[1,0]
	v_pk_add_f32 v[18:19], v[18:19], v[196:197] op_sel_hi:[1,0] neg_lo:[0,1] neg_hi:[0,1]
	v_pk_add_f32 v[4:5], v[4:5], v[196:197] op_sel_hi:[1,0] neg_lo:[0,1] neg_hi:[0,1]
	v_pk_mul_f32 v[18:19], v[196:197], v[18:19] op_sel:[1,0]
	v_pk_mul_f32 v[4:5], v[196:197], v[4:5] op_sel:[1,0]
	v_pk_add_f32 v[6:7], v[6:7], v[196:197] op_sel_hi:[1,0] neg_lo:[0,1] neg_hi:[0,1]
	v_pk_add_f32 v[0:1], v[0:1], v[196:197] op_sel_hi:[1,0] neg_lo:[0,1] neg_hi:[0,1]
	v_pk_mul_f32 v[6:7], v[196:197], v[6:7] op_sel:[1,0]
	v_pk_add_f32 v[2:3], v[2:3], v[196:197] op_sel_hi:[1,0] neg_lo:[0,1] neg_hi:[0,1]
	v_pk_mul_f32 v[0:1], v[196:197], v[0:1] op_sel:[1,0]
	v_pk_mul_f32 v[2:3], v[196:197], v[2:3] op_sel:[1,0]
	s_waitcnt vmcnt(2)
	v_pk_fma_f32 v[122:123], v[162:163], v[134:135], v[166:167]
	v_pk_fma_f32 v[124:125], v[164:165], v[126:127], v[168:169]
	s_waitcnt vmcnt(0)
; __device__ __forceinline__ unsigned pk2(float lo, float hi) { f32x2_t v = {lo, hi}; bf16x2_t b = __builtin_convertvector(v, bf16x2_t); return __builtin_bit_cast(unsigned, b); }
;     __device__ __forceinline__ void fused(f32x4 (&acc)[2][2][4][2], const Unit& u, int wr, int wc, int fr, int fq, PG8_LAS unsigned char* lds, int wid, int lane) const {
;     ...
; #pragma unroll
;         for (int bj = 0; bj < 2; ++bj) {
;             const int col = u.pn * 256 + bj * 128 + wc * 32 + fq * 8;
;             float gg[8], bb[8]; ld8f32(gam + col, gg); ld8f32(bet + col, bb);
; #pragma unroll
;             for (int ai = 0; ai < 2; ++ai)
; #pragma unroll
;                 for (int m = 0; m < 4; ++m) {
;                     const int rl = ai * 128 + wr * 64 + m * 16 + fr;
;                     const float mu = S[rl * 2], rs = S[rl * 2 + 1];
;                     const f32x4 v0 = acc[ai][bj][m][0], v1 = acc[ai][bj][m][1];
;                     float y[8];
; #pragma unroll
;                     for (int j = 0; j < 4; ++j) { y[j] = (v0[j] - mu) * rs * gg[j] + bb[j]; y[4 + j] = (v1[j] - mu) * rs * gg[4 + j] + bb[4 + j]; }
;                     const size_t off = (size_t)(u.pm * 256 + rl) * 1024 + col;
;                     if (of32) { *(float4*)(of32 + off) = make_float4(y[0], y[1], y[2], y[3]); *(float4*)(of32 + off + 4) = make_float4(y[4], y[5], y[6], y[7]); }
;                     if (obf) { uint4 o; o.x = pk2(y[0], y[1]); o.y = pk2(y[2], y[3]); o.z = pk2(y[4], y[5]); o.w = pk2(y[6], y[7]); *(uint4*)(obf + off) = o; }
;                 }
;         }
	v_pk_fma_f32 v[108:109], v[180:181], v[8:9], v[176:177]
	v_pk_mul_f32 v[8:9], v[154:155], v[170:171] op_sel:[1,0]
	v_pk_fma_f32 v[14:15], v[164:165], v[106:107], v[168:169]
	v_pk_fma_f32 v[192:193], v[180:181], v[8:9], v[176:177]
	v_pk_add_f32 v[8:9], v[98:99], v[146:147] op_sel_hi:[1,0] neg_lo:[0,1] neg_hi:[0,1]
	v_pk_fma_f32 v[106:107], v[178:179], v[182:183], v[174:175]
	v_pk_mul_f32 v[8:9], v[146:147], v[8:9] op_sel:[1,0]
	v_pk_fma_f32 v[182:183], v[178:179], v[184:185], v[174:175]
	v_pk_fma_f32 v[184:185], v[180:181], v[186:187], v[176:177]
	v_pk_fma_f32 v[186:187], v[162:163], v[114:115], v[166:167]
	v_pk_fma_f32 v[188:189], v[164:165], v[110:111], v[168:169]
	global_store_dwordx4 v[160:161], v[122:125], off
	global_store_dwordx4 v[160:161], v[182:185], off offset:16
	global_store_dwordx4 v[156:157], v[186:189], off
	v_pk_fma_f32 v[122:123], v[162:163], v[8:9], v[166:167]
	v_pk_add_f32 v[8:9], v[94:95], v[146:147] op_sel_hi:[1,0] neg_lo:[0,1] neg_hi:[0,1]
	v_pk_fma_f32 v[190:191], v[178:179], v[190:191], v[174:175]
	v_pk_mul_f32 v[8:9], v[146:147], v[8:9] op_sel:[1,0]
	global_store_dwordx4 v[156:157], v[190:193], off offset:16
	v_pk_fma_f32 v[124:125], v[164:165], v[8:9], v[168:169]
	v_pk_add_f32 v[8:9], v[92:93], v[146:147] op_sel_hi:[1,0] neg_lo:[0,1] neg_hi:[0,1]
	v_pk_fma_f32 v[12:13], v[162:163], v[18:19], v[166:167]
	v_pk_mul_f32 v[8:9], v[146:147], v[8:9] op_sel:[1,0]
	global_store_dwordx4 v[152:153], v[122:125], off
	v_pk_fma_f32 v[92:93], v[178:179], v[8:9], v[174:175]
	v_pk_add_f32 v[8:9], v[90:91], v[146:147] op_sel_hi:[1,0] neg_lo:[0,1] neg_hi:[0,1]
	s_nop 0
	v_pk_mul_f32 v[8:9], v[146:147], v[8:9] op_sel:[1,0]
	s_nop 0
	v_pk_fma_f32 v[94:95], v[180:181], v[8:9], v[176:177]
	v_pk_add_f32 v[8:9], v[82:83], v[142:143] op_sel_hi:[1,0] neg_lo:[0,1] neg_hi:[0,1]
	global_store_dwordx4 v[152:153], v[92:95], off offset:16
	v_pk_mul_f32 v[8:9], v[142:143], v[8:9] op_sel:[1,0]
	s_nop 0
	v_pk_fma_f32 v[90:91], v[162:163], v[8:9], v[166:167]
	v_pk_add_f32 v[8:9], v[78:79], v[142:143] op_sel_hi:[1,0] neg_lo:[0,1] neg_hi:[0,1]
	s_nop 0
	v_pk_mul_f32 v[8:9], v[142:143], v[8:9] op_sel:[1,0]
	s_nop 0
	v_pk_fma_f32 v[92:93], v[164:165], v[8:9], v[168:169]
	v_pk_add_f32 v[8:9], v[76:77], v[142:143] op_sel_hi:[1,0] neg_lo:[0,1] neg_hi:[0,1]
	global_store_dwordx4 v[144:145], v[90:93], off
	v_pk_mul_f32 v[8:9], v[142:143], v[8:9] op_sel:[1,0]
	s_nop 0
	v_pk_fma_f32 v[76:77], v[178:179], v[8:9], v[174:175]
	v_pk_add_f32 v[8:9], v[74:75], v[142:143] op_sel_hi:[1,0] neg_lo:[0,1] neg_hi:[0,1]
	s_nop 0
	v_pk_mul_f32 v[8:9], v[142:143], v[8:9] op_sel:[1,0]
	s_nop 0
	v_pk_fma_f32 v[78:79], v[180:181], v[8:9], v[176:177]
	v_pk_add_f32 v[8:9], v[66:67], v[138:139] op_sel_hi:[1,0] neg_lo:[0,1] neg_hi:[0,1]
	global_store_dwordx4 v[144:145], v[76:79], off offset:16
	v_pk_mul_f32 v[8:9], v[138:139], v[8:9] op_sel:[1,0]
	s_nop 0
	v_pk_fma_f32 v[74:75], v[162:163], v[8:9], v[166:167]
	v_pk_add_f32 v[8:9], v[62:63], v[138:139] op_sel_hi:[1,0] neg_lo:[0,1] neg_hi:[0,1]
	s_nop 0
	v_pk_mul_f32 v[8:9], v[138:139], v[8:9] op_sel:[1,0]
	s_nop 0
	v_pk_fma_f32 v[76:77], v[164:165], v[8:9], v[168:169]
	v_pk_add_f32 v[8:9], v[60:61], v[138:139] op_sel_hi:[1,0] neg_lo:[0,1] neg_hi:[0,1]
	global_store_dwordx4 v[140:141], v[74:77], off
	v_pk_mul_f32 v[8:9], v[138:139], v[8:9] op_sel:[1,0]
	s_nop 0
	v_pk_fma_f32 v[60:61], v[178:179], v[8:9], v[174:175]
	v_pk_add_f32 v[8:9], v[58:59], v[138:139] op_sel_hi:[1,0] neg_lo:[0,1] neg_hi:[0,1]
	s_nop 0
	v_pk_mul_f32 v[8:9], v[138:139], v[8:9] op_sel:[1,0]
	s_nop 0
	v_pk_fma_f32 v[62:63], v[180:181], v[8:9], v[176:177]
	v_pk_add_f32 v[8:9], v[50:51], v[132:133] op_sel_hi:[1,0] neg_lo:[0,1] neg_hi:[0,1]
	global_store_dwordx4 v[140:141], v[60:63], off offset:16
	v_pk_mul_f32 v[8:9], v[132:133], v[8:9] op_sel:[1,0]
	s_nop 0
	v_pk_fma_f32 v[58:59], v[162:163], v[8:9], v[166:167]
	v_pk_add_f32 v[8:9], v[46:47], v[132:133] op_sel_hi:[1,0] neg_lo:[0,1] neg_hi:[0,1]
	s_nop 0
	v_pk_mul_f32 v[8:9], v[132:133], v[8:9] op_sel:[1,0]
	s_nop 0
	v_pk_fma_f32 v[60:61], v[164:165], v[8:9], v[168:169]
	v_pk_add_f32 v[8:9], v[44:45], v[132:133] op_sel_hi:[1,0] neg_lo:[0,1] neg_hi:[0,1]
	global_store_dwordx4 v[136:137], v[58:61], off
	v_pk_mul_f32 v[8:9], v[132:133], v[8:9] op_sel:[1,0]
	s_nop 0
	v_pk_fma_f32 v[44:45], v[178:179], v[8:9], v[174:175]
	v_pk_add_f32 v[8:9], v[42:43], v[132:133] op_sel_hi:[1,0] neg_lo:[0,1] neg_hi:[0,1]
	s_nop 0
	v_pk_mul_f32 v[8:9], v[132:133], v[8:9] op_sel:[1,0]
	s_nop 0
	v_pk_fma_f32 v[46:47], v[180:181], v[8:9], v[176:177]
	v_pk_add_f32 v[8:9], v[34:35], v[128:129] op_sel_hi:[1,0] neg_lo:[0,1] neg_hi:[0,1]
	global_store_dwordx4 v[136:137], v[44:47], off offset:16
	v_pk_mul_f32 v[8:9], v[128:129], v[8:9] op_sel:[1,0]
	s_nop 0
	v_pk_fma_f32 v[42:43], v[162:163], v[8:9], v[166:167]
	v_pk_add_f32 v[8:9], v[28:29], v[128:129] op_sel_hi:[1,0] neg_lo:[0,1] neg_hi:[0,1]
	s_nop 0
	v_pk_mul_f32 v[8:9], v[128:129], v[8:9] op_sel:[1,0]
	s_nop 0
	v_pk_fma_f32 v[44:45], v[164:165], v[8:9], v[168:169]
	v_pk_add_f32 v[8:9], v[30:31], v[128:129] op_sel_hi:[1,0] neg_lo:[0,1] neg_hi:[0,1]
	global_store_dwordx4 v[130:131], v[42:45], off
	v_pk_mul_f32 v[8:9], v[128:129], v[8:9] op_sel:[1,0]
	s_nop 0
	v_pk_fma_f32 v[28:29], v[178:179], v[8:9], v[174:175]
	v_pk_add_f32 v[8:9], v[26:27], v[128:129] op_sel_hi:[1,0] neg_lo:[0,1] neg_hi:[0,1]
	s_nop 0
	v_pk_mul_f32 v[8:9], v[128:129], v[8:9] op_sel:[1,0]
	s_nop 0
	v_pk_fma_f32 v[30:31], v[180:181], v[8:9], v[176:177]
	global_store_dwordx4 v[130:131], v[28:31], off offset:16
	global_store_dwordx4 v[10:11], v[12:15], off
	global_store_dwordx4 v[10:11], v[106:109], off offset:16
	s_nop 1
; __device__ __forceinline__ unsigned pk2(float lo, float hi) { f32x2_t v = {lo, hi}; bf16x2_t b = __builtin_convertvector(v, bf16x2_t); return __builtin_bit_cast(unsigned, b); }
;     __device__ __forceinline__ void fused(f32x4 (&acc)[2][2][4][2], const Unit& u, int wr, int wc, int fr, int fq, PG8_LAS unsigned char* lds, int wid, int lane) const {
;     ...
; #pragma unroll
;         for (int bj = 0; bj < 2; ++bj) {
;             const int col = u.pn * 256 + bj * 128 + wc * 32 + fq * 8;
;             float gg[8], bb[8]; ld8f32(gam + col, gg); ld8f32(bet + col, bb);
; #pragma unroll
;             for (int ai = 0; ai < 2; ++ai)
; #pragma unroll
;                 for (int m = 0; m < 4; ++m) {
;                     const int rl = ai * 128 + wr * 64 + m * 16 + fr;
;                     const float mu = S[rl * 2], rs = S[rl * 2 + 1];
;                     const f32x4 v0 = acc[ai][bj][m][0], v1 = acc[ai][bj][m][1];
;                     float y[8];
; #pragma unroll
;                     for (int j = 0; j < 4; ++j) { y[j] = (v0[j] - mu) * rs * gg[j] + bb[j]; y[4 + j] = (v1[j] - mu) * rs * gg[4 + j] + bb[4 + j]; }
;                     const size_t off = (size_t)(u.pm * 256 + rl) * 1024 + col;
;                     if (of32) { *(float4*)(of32 + off) = make_float4(y[0], y[1], y[2], y[3]); *(float4*)(of32 + off + 4) = make_float4(y[4], y[5], y[6], y[7]); }
;                     if (obf) { uint4 o; o.x = pk2(y[0], y[1]); o.y = pk2(y[2], y[3]); o.z = pk2(y[4], y[5]); o.w = pk2(y[6], y[7]); *(uint4*)(obf + off) = o; }
;                 }
	v_mov_b64_e32 v[12:13], v[200:201]
	v_mov_b64_e32 v[14:15], v[202:203]
	s_nop 0
	v_mov_b64_e32 v[26:27], v[204:205]
	v_mov_b64_e32 v[28:29], v[206:207]
	v_mov_b64_e32 v[42:43], v[208:209]
	v_mov_b64_e32 v[44:45], v[210:211]
	v_mov_b64_e32 v[58:59], v[212:213]
	v_mov_b64_e32 v[60:61], v[214:215]
	v_pk_add_f32 v[8:9], v[120:121], v[158:159] op_sel_hi:[1,0] neg_lo:[0,1] neg_hi:[0,1]
	v_pk_fma_f32 v[4:5], v[4:5], v[12:13], v[26:27]
	v_pk_mul_f32 v[8:9], v[158:159], v[8:9] op_sel:[1,0]
	v_pk_fma_f32 v[6:7], v[6:7], v[14:15], v[28:29]
	v_pk_fma_f32 v[74:75], v[8:9], v[12:13], v[26:27]
	v_pk_add_f32 v[8:9], v[118:119], v[158:159] op_sel_hi:[1,0] neg_lo:[0,1] neg_hi:[0,1]
	v_pk_fma_f32 v[0:1], v[0:1], v[58:59], v[42:43]
	v_pk_mul_f32 v[8:9], v[158:159], v[8:9] op_sel:[1,0]
	v_pk_fma_f32 v[2:3], v[2:3], v[60:61], v[44:45]
	v_pk_fma_f32 v[76:77], v[8:9], v[14:15], v[28:29]
	v_pk_add_f32 v[8:9], v[116:117], v[158:159] op_sel_hi:[1,0] neg_lo:[0,1] neg_hi:[0,1]
	global_store_dwordx4 v[160:161], v[74:77], off offset:512
	v_pk_mul_f32 v[8:9], v[158:159], v[8:9] op_sel:[1,0]
	s_nop 0
	v_pk_fma_f32 v[74:75], v[8:9], v[58:59], v[42:43]
	v_pk_add_f32 v[8:9], v[112:113], v[158:159] op_sel_hi:[1,0] neg_lo:[0,1] neg_hi:[0,1]
	s_nop 0
	v_pk_mul_f32 v[8:9], v[158:159], v[8:9] op_sel:[1,0]
	s_nop 0
	v_pk_fma_f32 v[76:77], v[8:9], v[60:61], v[44:45]
	v_pk_add_f32 v[8:9], v[100:101], v[154:155] op_sel_hi:[1,0] neg_lo:[0,1] neg_hi:[0,1]
	global_store_dwordx4 v[160:161], v[74:77], off offset:528
	v_pk_mul_f32 v[8:9], v[154:155], v[8:9] op_sel:[1,0]
	s_nop 0
	v_pk_fma_f32 v[74:75], v[8:9], v[12:13], v[26:27]
	v_pk_add_f32 v[8:9], v[104:105], v[154:155] op_sel_hi:[1,0] neg_lo:[0,1] neg_hi:[0,1]
	s_nop 0
	v_pk_mul_f32 v[8:9], v[154:155], v[8:9] op_sel:[1,0]
	s_nop 0
	v_pk_fma_f32 v[76:77], v[8:9], v[14:15], v[28:29]
	v_pk_add_f32 v[8:9], v[102:103], v[154:155] op_sel_hi:[1,0] neg_lo:[0,1] neg_hi:[0,1]
	global_store_dwordx4 v[156:157], v[74:77], off offset:512
	v_pk_mul_f32 v[8:9], v[154:155], v[8:9] op_sel:[1,0]
	s_nop 0
	v_pk_fma_f32 v[74:75], v[8:9], v[58:59], v[42:43]
	v_pk_add_f32 v[8:9], v[96:97], v[154:155] op_sel_hi:[1,0] neg_lo:[0,1] neg_hi:[0,1]
	s_nop 0
	v_pk_mul_f32 v[8:9], v[154:155], v[8:9] op_sel:[1,0]
	s_nop 0
	v_pk_fma_f32 v[76:77], v[8:9], v[60:61], v[44:45]
	v_pk_add_f32 v[8:9], v[84:85], v[146:147] op_sel_hi:[1,0] neg_lo:[0,1] neg_hi:[0,1]
	global_store_dwordx4 v[156:157], v[74:77], off offset:528
	v_pk_mul_f32 v[8:9], v[146:147], v[8:9] op_sel:[1,0]
	s_nop 0
	v_pk_fma_f32 v[74:75], v[8:9], v[12:13], v[26:27]
	v_pk_add_f32 v[8:9], v[88:89], v[146:147] op_sel_hi:[1,0] neg_lo:[0,1] neg_hi:[0,1]
	s_nop 0
	v_pk_mul_f32 v[8:9], v[146:147], v[8:9] op_sel:[1,0]
	s_nop 0
	v_pk_fma_f32 v[76:77], v[8:9], v[14:15], v[28:29]
	v_pk_add_f32 v[8:9], v[86:87], v[146:147] op_sel_hi:[1,0] neg_lo:[0,1] neg_hi:[0,1]
	global_store_dwordx4 v[152:153], v[74:77], off offset:512
	v_pk_mul_f32 v[8:9], v[146:147], v[8:9] op_sel:[1,0]
	s_nop 0
	v_pk_fma_f32 v[74:75], v[8:9], v[58:59], v[42:43]
	v_pk_add_f32 v[8:9], v[80:81], v[146:147] op_sel_hi:[1,0] neg_lo:[0,1] neg_hi:[0,1]
	s_nop 0
	v_pk_mul_f32 v[8:9], v[146:147], v[8:9] op_sel:[1,0]
	s_nop 0
	v_pk_fma_f32 v[76:77], v[8:9], v[60:61], v[44:45]
	v_pk_add_f32 v[8:9], v[68:69], v[142:143] op_sel_hi:[1,0] neg_lo:[0,1] neg_hi:[0,1]
	global_store_dwordx4 v[152:153], v[74:77], off offset:528
	v_pk_mul_f32 v[8:9], v[142:143], v[8:9] op_sel:[1,0]
	s_nop 0
	v_pk_fma_f32 v[66:67], v[8:9], v[12:13], v[26:27]
	v_pk_add_f32 v[8:9], v[72:73], v[142:143] op_sel_hi:[1,0] neg_lo:[0,1] neg_hi:[0,1]
; __device__ __forceinline__ unsigned pk2(float lo, float hi) { f32x2_t v = {lo, hi}; bf16x2_t b = __builtin_convertvector(v, bf16x2_t); return __builtin_bit_cast(unsigned, b); }
;     __device__ __forceinline__ void fused(f32x4 (&acc)[2][2][4][2], const Unit& u, int wr, int wc, int fr, int fq, PG8_LAS unsigned char* lds, int wid, int lane) const {
;     ...
;             for (int ai = 0; ai < 2; ++ai)
; #pragma unroll
;                 for (int m = 0; m < 4; ++m) {
;                     const int rl = ai * 128 + wr * 64 + m * 16 + fr;
;                     const float mu = S[rl * 2], rs = S[rl * 2 + 1];
;                     const f32x4 v0 = acc[ai][bj][m][0], v1 = acc[ai][bj][m][1];
;                     float y[8];
; #pragma unroll
;                     for (int j = 0; j < 4; ++j) { y[j] = (v0[j] - mu) * rs * gg[j] + bb[j]; y[4 + j] = (v1[j] - mu) * rs * gg[4 + j] + bb[4 + j]; }
;                     const size_t off = (size_t)(u.pm * 256 + rl) * 1024 + col;
;                     if (of32) { *(float4*)(of32 + off) = make_float4(y[0], y[1], y[2], y[3]); *(float4*)(of32 + off + 4) = make_float4(y[4], y[5], y[6], y[7]); }
;                     if (obf) { uint4 o; o.x = pk2(y[0], y[1]); o.y = pk2(y[2], y[3]); o.z = pk2(y[4], y[5]); o.w = pk2(y[6], y[7]); *(uint4*)(obf + off) = o; }
;                 }
	s_nop 0
	v_pk_mul_f32 v[8:9], v[142:143], v[8:9] op_sel:[1,0]
	s_nop 0
	v_pk_fma_f32 v[68:69], v[8:9], v[14:15], v[28:29]
	v_pk_add_f32 v[8:9], v[70:71], v[142:143] op_sel_hi:[1,0] neg_lo:[0,1] neg_hi:[0,1]
	global_store_dwordx4 v[144:145], v[66:69], off offset:512
	v_pk_mul_f32 v[8:9], v[142:143], v[8:9] op_sel:[1,0]
	s_nop 0
	v_pk_fma_f32 v[62:63], v[8:9], v[58:59], v[42:43]
	v_pk_add_f32 v[8:9], v[64:65], v[142:143] op_sel_hi:[1,0] neg_lo:[0,1] neg_hi:[0,1]
	s_nop 0
	v_pk_mul_f32 v[8:9], v[142:143], v[8:9] op_sel:[1,0]
	s_nop 0
	v_pk_fma_f32 v[64:65], v[8:9], v[60:61], v[44:45]
	v_pk_add_f32 v[8:9], v[52:53], v[138:139] op_sel_hi:[1,0] neg_lo:[0,1] neg_hi:[0,1]
	global_store_dwordx4 v[144:145], v[62:65], off offset:528
	v_pk_mul_f32 v[8:9], v[138:139], v[8:9] op_sel:[1,0]
	s_nop 0
	v_pk_fma_f32 v[50:51], v[8:9], v[12:13], v[26:27]
	v_pk_add_f32 v[8:9], v[56:57], v[138:139] op_sel_hi:[1,0] neg_lo:[0,1] neg_hi:[0,1]
	s_nop 0
	v_pk_mul_f32 v[8:9], v[138:139], v[8:9] op_sel:[1,0]
	s_nop 0
	v_pk_fma_f32 v[52:53], v[8:9], v[14:15], v[28:29]
	v_pk_add_f32 v[8:9], v[54:55], v[138:139] op_sel_hi:[1,0] neg_lo:[0,1] neg_hi:[0,1]
	global_store_dwordx4 v[140:141], v[50:53], off offset:512
	v_pk_mul_f32 v[8:9], v[138:139], v[8:9] op_sel:[1,0]
	s_nop 0
	v_pk_fma_f32 v[46:47], v[8:9], v[58:59], v[42:43]
	v_pk_add_f32 v[8:9], v[48:49], v[138:139] op_sel_hi:[1,0] neg_lo:[0,1] neg_hi:[0,1]
	s_nop 0
	v_pk_mul_f32 v[8:9], v[138:139], v[8:9] op_sel:[1,0]
	s_nop 0
	v_pk_fma_f32 v[48:49], v[8:9], v[60:61], v[44:45]
	v_pk_add_f32 v[8:9], v[40:41], v[132:133] op_sel_hi:[1,0] neg_lo:[0,1] neg_hi:[0,1]
	global_store_dwordx4 v[140:141], v[46:49], off offset:528
	v_pk_mul_f32 v[8:9], v[132:133], v[8:9] op_sel:[1,0]
	s_nop 0
	v_pk_fma_f32 v[46:47], v[8:9], v[12:13], v[26:27]
	v_pk_add_f32 v[8:9], v[38:39], v[132:133] op_sel_hi:[1,0] neg_lo:[0,1] neg_hi:[0,1]
	s_nop 0
	v_pk_mul_f32 v[8:9], v[132:133], v[8:9] op_sel:[1,0]
	s_nop 0
	v_pk_fma_f32 v[48:49], v[8:9], v[14:15], v[28:29]
	v_pk_add_f32 v[8:9], v[36:37], v[132:133] op_sel_hi:[1,0] neg_lo:[0,1] neg_hi:[0,1]
	global_store_dwordx4 v[136:137], v[46:49], off offset:512
	v_pk_mul_f32 v[8:9], v[132:133], v[8:9] op_sel:[1,0]
	s_nop 0
	v_pk_fma_f32 v[30:31], v[8:9], v[58:59], v[42:43]
	v_pk_add_f32 v[8:9], v[32:33], v[132:133] op_sel_hi:[1,0] neg_lo:[0,1] neg_hi:[0,1]
	s_nop 0
	v_pk_mul_f32 v[8:9], v[132:133], v[8:9] op_sel:[1,0]
	s_nop 0
	v_pk_fma_f32 v[32:33], v[8:9], v[60:61], v[44:45]
	v_pk_add_f32 v[8:9], v[24:25], v[128:129] op_sel_hi:[1,0] neg_lo:[0,1] neg_hi:[0,1]
	global_store_dwordx4 v[136:137], v[30:33], off offset:528
	v_pk_mul_f32 v[8:9], v[128:129], v[8:9] op_sel:[1,0]
	s_nop 0
	v_pk_fma_f32 v[12:13], v[8:9], v[12:13], v[26:27]
	v_pk_add_f32 v[8:9], v[22:23], v[128:129] op_sel_hi:[1,0] neg_lo:[0,1] neg_hi:[0,1]
	s_nop 0
	v_pk_mul_f32 v[8:9], v[128:129], v[8:9] op_sel:[1,0]
	s_nop 0
	v_pk_fma_f32 v[14:15], v[8:9], v[14:15], v[28:29]
	v_pk_add_f32 v[8:9], v[20:21], v[128:129] op_sel_hi:[1,0] neg_lo:[0,1] neg_hi:[0,1]
	global_store_dwordx4 v[130:131], v[12:15], off offset:512
	v_pk_mul_f32 v[8:9], v[128:129], v[8:9] op_sel:[1,0]
	s_nop 0
	v_pk_fma_f32 v[12:13], v[8:9], v[58:59], v[42:43]
	v_pk_add_f32 v[8:9], v[16:17], v[128:129] op_sel_hi:[1,0] neg_lo:[0,1] neg_hi:[0,1]
	s_nop 0
	v_pk_mul_f32 v[8:9], v[128:129], v[8:9] op_sel:[1,0]
	s_nop 0
	v_pk_fma_f32 v[14:15], v[8:9], v[60:61], v[44:45]
	global_store_dwordx4 v[130:131], v[12:15], off offset:528
	global_store_dwordx4 v[10:11], v[4:7], off offset:512
	global_store_dwordx4 v[10:11], v[0:3], off offset:528
